# acquire invalidate moved to just before the leader's first poll of the release word (was: after arrival); rest as previous stack
# speedup vs baseline: 1.0199x; 1.0066x over previous
; __device__ __forceinline__ unsigned xb_ld(unsigned* p)              { return __hip_atomic_load(p, __ATOMIC_RELAXED, __HIP_MEMORY_SCOPE_AGENT); }
; #define XB_SPIN(cond, bar) do { unsigned _sp = 0; while (cond) { __builtin_amdgcn_s_sleep(1); \
;     if ((++_sp & 255u) == 0u) { if (xb_ld(&(bar)[XB_TMO])) break; if (_sp > XB_SPIN_CAP) { atomicAdd(&(bar)[XB_TMO], 1u); break; } } } } while (0)
; __device__ __forceinline__ void xcd_barrier(const XcdBarrier& b, bool leader) {
;     ...
;         XB_SPIN(xb_ld(&bar[XB_TOPGEN]) == gen, bar);
;         __builtin_amdgcn_fence(__ATOMIC_ACQUIRE, "agent");
.LBB0_77:
	s_or_b64 exec, exec, s[6:7]
	s_waitcnt lgkmcnt(0)
	v_mov_b32_e32 v1, 0x3000
	buffer_inv sc1
	global_load_dword v1, v1, s[90:91] offset:1280 sc1
	s_add_u32 s8, s90, 0x3500
	s_addc_u32 s9, s91, 0
	s_waitcnt vmcnt(0)
	v_cmp_eq_u32_e32 vcc, v1, v0
	s_and_saveexec_b64 s[6:7], vcc
	s_cbranch_execz .LBB0_89
	s_mov_b32 s0, 1
	s_mov_b64 s[10:11], 0
	v_mov_b32_e32 v1, 0
	s_branch .LBB0_80

; __device__ __forceinline__ unsigned xb_ld(unsigned* p)              { return __hip_atomic_load(p, __ATOMIC_RELAXED, __HIP_MEMORY_SCOPE_AGENT); }
; #define XB_SPIN(cond, bar) do { unsigned _sp = 0; while (cond) { __builtin_amdgcn_s_sleep(1); \
;     if ((++_sp & 255u) == 0u) { if (xb_ld(&(bar)[XB_TMO])) break; if (_sp > XB_SPIN_CAP) { atomicAdd(&(bar)[XB_TMO], 1u); break; } } } } while (0)
; __device__ __forceinline__ void xcd_barrier(const XcdBarrier& b, bool leader) {
;     ...
;         XB_SPIN(xb_ld(&bar[XB_TOPGEN]) == gen, bar);
;         __builtin_amdgcn_fence(__ATOMIC_ACQUIRE, "agent");
.LBB0_185:
	s_or_b64 exec, exec, s[6:7]
	s_waitcnt lgkmcnt(0)
	v_mov_b32_e32 v1, 0x3000
	buffer_inv sc1
	global_load_dword v1, v1, s[90:91] offset:1280 sc1
	s_add_u32 s10, s90, 0x3500
	s_addc_u32 s11, s91, 0
	s_waitcnt vmcnt(0)
	v_cmp_eq_u32_e32 vcc, v1, v0
	s_and_saveexec_b64 s[6:7], vcc
	s_cbranch_execz .LBB0_197
	s_mov_b32 s36, 1
	s_mov_b64 s[12:13], 0
	v_mov_b32_e32 v1, 0
	s_branch .LBB0_188

; __device__ __forceinline__ unsigned xb_ld(unsigned* p)              { return __hip_atomic_load(p, __ATOMIC_RELAXED, __HIP_MEMORY_SCOPE_AGENT); }
; #define XB_SPIN(cond, bar) do { unsigned _sp = 0; while (cond) { __builtin_amdgcn_s_sleep(1); \
;     if ((++_sp & 255u) == 0u) { if (xb_ld(&(bar)[XB_TMO])) break; if (_sp > XB_SPIN_CAP) { atomicAdd(&(bar)[XB_TMO], 1u); break; } } } } while (0)
; __device__ __forceinline__ void xcd_barrier(const XcdBarrier& b, bool leader) {
;     ...
;         XB_SPIN(xb_ld(&bar[XB_TOPGEN]) == gen, bar);
;         __builtin_amdgcn_fence(__ATOMIC_ACQUIRE, "agent");
.LBB0_235:
	s_or_b64 exec, exec, s[6:7]
	s_waitcnt lgkmcnt(0)
	v_mov_b32_e32 v1, 0x3000
	buffer_inv sc1
	global_load_dword v1, v1, s[90:91] offset:1280 sc1
	s_add_u32 s10, s90, 0x3500
	s_addc_u32 s11, s91, 0
	s_waitcnt vmcnt(0)
	v_cmp_eq_u32_e32 vcc, v1, v0
	s_and_saveexec_b64 s[6:7], vcc
	s_cbranch_execz .LBB0_247
	s_mov_b32 s3, 1
	s_mov_b64 s[12:13], 0
	v_mov_b32_e32 v1, 0
	s_branch .LBB0_238

; __device__ __forceinline__ unsigned xb_ld(unsigned* p)              { return __hip_atomic_load(p, __ATOMIC_RELAXED, __HIP_MEMORY_SCOPE_AGENT); }
; #define XB_SPIN(cond, bar) do { unsigned _sp = 0; while (cond) { __builtin_amdgcn_s_sleep(1); \
;     if ((++_sp & 255u) == 0u) { if (xb_ld(&(bar)[XB_TMO])) break; if (_sp > XB_SPIN_CAP) { atomicAdd(&(bar)[XB_TMO], 1u); break; } } } } while (0)
; __device__ __forceinline__ void xcd_barrier(const XcdBarrier& b, bool leader) {
;     ...
;         XB_SPIN(xb_ld(&bar[XB_TOPGEN]) == gen, bar);
;         __builtin_amdgcn_fence(__ATOMIC_ACQUIRE, "agent");
.LBB0_328:
	s_or_b64 exec, exec, s[6:7]
	s_waitcnt lgkmcnt(0)
	v_mov_b32_e32 v1, 0x3000
	buffer_inv sc1
	global_load_dword v1, v1, s[90:91] offset:1280 sc1
	s_add_u32 s8, s90, 0x3500
	s_addc_u32 s9, s91, 0
	s_waitcnt vmcnt(0)
	v_cmp_eq_u32_e32 vcc, v1, v0
	s_and_saveexec_b64 s[6:7], vcc
	s_cbranch_execz .LBB0_340
	s_mov_b32 s40, 1
	s_mov_b64 s[10:11], 0
	v_mov_b32_e32 v1, 0
	s_branch .LBB0_331

; __device__ __forceinline__ unsigned xb_ld(unsigned* p)              { return __hip_atomic_load(p, __ATOMIC_RELAXED, __HIP_MEMORY_SCOPE_AGENT); }
; #define XB_SPIN(cond, bar) do { unsigned _sp = 0; while (cond) { __builtin_amdgcn_s_sleep(1); \
;     if ((++_sp & 255u) == 0u) { if (xb_ld(&(bar)[XB_TMO])) break; if (_sp > XB_SPIN_CAP) { atomicAdd(&(bar)[XB_TMO], 1u); break; } } } } while (0)
; __device__ __forceinline__ void xcd_barrier(const XcdBarrier& b, bool leader) {
;     ...
;         XB_SPIN(xb_ld(&bar[XB_TOPGEN]) == gen, bar);
;         __builtin_amdgcn_fence(__ATOMIC_ACQUIRE, "agent");
.LBB0_375:
	s_or_b64 exec, exec, s[8:9]
	s_waitcnt lgkmcnt(0)
	v_mov_b32_e32 v1, 0x3000
	buffer_inv sc1
	global_load_dword v1, v1, s[90:91] offset:1280 sc1
	s_add_u32 s10, s90, 0x3500
	s_addc_u32 s11, s91, 0
	s_waitcnt vmcnt(0)
	v_cmp_eq_u32_e32 vcc, v1, v0
	s_and_saveexec_b64 s[8:9], vcc
	s_cbranch_execz .LBB0_387
	s_mov_b32 s34, 1
	s_mov_b64 s[22:23], 0
	v_mov_b32_e32 v1, 0
	s_branch .LBB0_378

; __device__ __forceinline__ unsigned xb_ld(unsigned* p)              { return __hip_atomic_load(p, __ATOMIC_RELAXED, __HIP_MEMORY_SCOPE_AGENT); }
; #define XB_SPIN(cond, bar) do { unsigned _sp = 0; while (cond) { __builtin_amdgcn_s_sleep(1); \
;     if ((++_sp & 255u) == 0u) { if (xb_ld(&(bar)[XB_TMO])) break; if (_sp > XB_SPIN_CAP) { atomicAdd(&(bar)[XB_TMO], 1u); break; } } } } while (0)
; __device__ __forceinline__ void xcd_barrier(const XcdBarrier& b, bool leader) {
;     ...
;         XB_SPIN(xb_ld(&bar[XB_TOPGEN]) == gen, bar);
;         __builtin_amdgcn_fence(__ATOMIC_ACQUIRE, "agent");
.LBB0_543:
	s_or_b64 exec, exec, s[10:11]
	s_waitcnt lgkmcnt(0)
	buffer_inv sc1
	global_load_dword v1, v147, s[36:37] sc1
	s_waitcnt vmcnt(0)
	v_cmp_eq_u32_e32 vcc, v1, v0
	s_and_saveexec_b64 s[10:11], vcc
	s_cbranch_execz .LBB0_555
	s_mov_b32 s8, 1
	s_mov_b64 s[42:43], 0
	s_branch .LBB0_546
